# mixer queue latch: waves skip the store-acknowledge drain when the finished unit has no pending publish
# speedup vs baseline: 1.0026x; 1.0026x over previous
.LBB0_809:
	s_or_b64 exec, exec, s[10:11]
	s_cmp_lg_u64 s[76:77], 0
	s_cbranch_scc0 .Lq_noack
	s_waitcnt vmcnt(0)
.Lq_noack:
	s_xor_b32 s80, s80, 4
	s_and_saveexec_b64 s[8:9], s[6:7]
	s_add_i32 s0, s80, 0
	s_add_i32 s0, s0, 0x27fe0
	v_mov_b32_e32 v1, s0
	ds_write_b32 v1, v0
	s_or_b64 exec, exec, s[8:9]
	s_cmp_lg_u64 s[76:77], 0
	s_cselect_b64 s[6:7], -1, 0
	s_xor_b64 s[8:9], vcc, -1
	s_and_b64 s[8:9], s[8:9], s[6:7]
	s_waitcnt lgkmcnt(0)
	s_barrier
	s_and_saveexec_b64 s[6:7], s[8:9]
	s_cbranch_execz .LBB0_641
	s_mov_b64 s[8:9], exec
	v_mbcnt_lo_u32_b32 v0, s8, 0
	v_mbcnt_hi_u32_b32 v0, s9, v0
	v_cmp_eq_u32_e32 vcc, 0, v0
	s_and_b64 s[10:11], exec, vcc
	s_mov_b64 exec, s[10:11]
	s_cbranch_execz .LBB0_641
	s_bcnt1_i32_b64 s0, s[8:9]
	s_mul_i32 s0, s18, s0
	v_mov_b32_e32 v0, s0
	global_atomic_add v33, v0, s[76:77]
	s_branch .LBB0_641
